# GEMM tile loops: accumulator zero-init with 64-bit moves (half the VALU instructions between tiles)
# speedup vs baseline: 1.0038x; 1.0038x over previous
.LBB0_184:
	s_add_i32 s52, s52, 1
	s_mov_b64 s[28:29], s[4:5]
	s_mul_i32 s4, s52, s85
	s_mov_b32 s54, s51
	s_add_i32 s51, s4, s86
	s_cmpk_lt_i32 s51, 0x200
	s_mov_b64 s[26:27], s[6:7]
	s_mov_b32 s6, s53
	s_cselect_b64 s[22:23], -1, 0
	s_ashr_i32 s53, s51, 6
	s_and_b64 s[4:5], s[22:23], exec
	s_cselect_b32 s4, s51, s24
	s_cselect_b32 s24, s53, s6
	s_ashr_i32 s5, s4, 31
	s_lshl_b64 s[4:5], s[4:5], 19
	s_add_u32 s6, s30, s4
	s_addc_u32 s7, s31, s5
	s_and_b64 s[4:5], s[22:23], exec
	s_cselect_b32 s55, s7, s27
	s_cselect_b32 s56, s6, s26
	s_ashr_i32 s25, s24, 31
	s_lshl_b64 s[4:5], s[24:25], 19
	s_add_u32 s4, s34, s4
	s_addc_u32 s5, s35, s5
	s_and_b64 s[24:25], s[22:23], exec
	s_cselect_b32 s57, s5, s29
	s_cselect_b32 s58, s4, s28
	s_add_u32 s24, s26, 0x40080
	s_addc_u32 s25, s27, 0
	s_add_u32 s59, s28, 0x100
	v_mov_b32_e32 v0, 0
	s_addc_u32 s60, s29, 0
	s_mov_b32 s61, -2
	v_mov_b32_e32 v1, v0
	v_mov_b64_e32 v[2:3], 0
	v_mov_b64_e32 v[4:5], 0
	v_mov_b64_e32 v[6:7], 0
	v_mov_b64_e32 v[8:9], 0
	v_mov_b64_e32 v[10:11], 0
	v_mov_b64_e32 v[12:13], 0
	v_mov_b64_e32 v[14:15], 0
	v_mov_b64_e32 v[20:21], 0
	v_mov_b64_e32 v[22:23], 0
	v_mov_b64_e32 v[28:29], 0
	v_mov_b64_e32 v[30:31], 0
	v_mov_b64_e32 v[36:37], 0
	v_mov_b64_e32 v[38:39], 0
	v_mov_b64_e32 v[44:45], 0
	v_mov_b64_e32 v[46:47], 0
	v_mov_b64_e32 v[16:17], 0
	v_mov_b64_e32 v[18:19], 0
	v_mov_b64_e32 v[24:25], 0
	v_mov_b64_e32 v[26:27], 0
	v_mov_b64_e32 v[32:33], 0
	v_mov_b64_e32 v[34:35], 0
	v_mov_b64_e32 v[40:41], 0
	v_mov_b64_e32 v[42:43], 0
	v_mov_b64_e32 v[48:49], 0
	v_mov_b64_e32 v[50:51], 0
	v_mov_b64_e32 v[52:53], 0
	v_mov_b64_e32 v[54:55], 0
	v_mov_b64_e32 v[56:57], 0
	v_mov_b64_e32 v[58:59], 0
	v_mov_b64_e32 v[60:61], 0
	v_mov_b64_e32 v[62:63], 0
	v_mov_b64_e32 v[64:65], 0
	v_mov_b64_e32 v[66:67], 0
	v_mov_b64_e32 v[68:69], 0
	v_mov_b64_e32 v[70:71], 0
	v_mov_b64_e32 v[72:73], 0
	v_mov_b64_e32 v[74:75], 0
	v_mov_b64_e32 v[76:77], 0
	v_mov_b64_e32 v[78:79], 0
	v_mov_b64_e32 v[84:85], 0
	v_mov_b64_e32 v[86:87], 0
	v_mov_b64_e32 v[92:93], 0
	v_mov_b64_e32 v[94:95], 0
	v_mov_b64_e32 v[100:101], 0
	v_mov_b64_e32 v[102:103], 0
	v_mov_b64_e32 v[108:109], 0
	v_mov_b64_e32 v[110:111], 0
	v_mov_b64_e32 v[80:81], 0
	v_mov_b64_e32 v[82:83], 0
	v_mov_b64_e32 v[88:89], 0
	v_mov_b64_e32 v[90:91], 0
	v_mov_b64_e32 v[96:97], 0
	v_mov_b64_e32 v[98:99], 0
	v_mov_b64_e32 v[104:105], 0
	v_mov_b64_e32 v[106:107], 0
	v_mov_b64_e32 v[112:113], 0
	v_mov_b64_e32 v[114:115], 0
	v_mov_b64_e32 v[116:117], 0
	v_mov_b64_e32 v[118:119], 0
	v_mov_b64_e32 v[120:121], 0
	v_mov_b64_e32 v[122:123], 0
	v_mov_b64_e32 v[124:125], 0
	v_mov_b64_e32 v[126:127], 0

.LBB0_349:
	s_ashr_i32 s11, s10, 31
	s_lshl_b64 s[2:3], s[10:11], 19
	s_add_u32 s14, s24, s2
	s_addc_u32 s15, s25, s3
	s_and_b64 s[2:3], s[44:45], exec
	s_cselect_b32 s11, s15, s19
	s_cselect_b32 s52, s14, s18
	s_ashr_i32 s13, s12, 31
	s_lshl_b64 s[2:3], s[12:13], 19
	s_add_u32 s16, s26, s2
	s_addc_u32 s17, s27, s3
	s_and_b64 s[2:3], s[44:45], exec
	s_cselect_b32 s13, s17, s21
	s_cselect_b32 s53, s16, s20
	s_add_u32 s18, s18, 0x40080
	s_addc_u32 s19, s19, 0
	s_add_u32 s54, s20, 0x100
	v_mov_b32_e32 v0, 0
	s_addc_u32 s55, s21, 0
	s_mov_b32 s56, -2
	v_mov_b32_e32 v1, v0
	v_mov_b64_e32 v[2:3], 0
	v_mov_b64_e32 v[4:5], 0
	v_mov_b64_e32 v[6:7], 0
	v_mov_b64_e32 v[8:9], 0
	v_mov_b64_e32 v[10:11], 0
	v_mov_b64_e32 v[12:13], 0
	v_mov_b64_e32 v[14:15], 0
	v_mov_b64_e32 v[16:17], 0
	v_mov_b64_e32 v[18:19], 0
	v_mov_b64_e32 v[24:25], 0
	v_mov_b64_e32 v[26:27], 0
	v_mov_b64_e32 v[32:33], 0
	v_mov_b64_e32 v[34:35], 0
	v_mov_b64_e32 v[40:41], 0
	v_mov_b64_e32 v[42:43], 0
	v_mov_b64_e32 v[20:21], 0
	v_mov_b64_e32 v[22:23], 0
	v_mov_b64_e32 v[28:29], 0
	v_mov_b64_e32 v[30:31], 0
	v_mov_b64_e32 v[36:37], 0
	v_mov_b64_e32 v[38:39], 0
	v_mov_b64_e32 v[44:45], 0
	v_mov_b64_e32 v[46:47], 0
	v_mov_b64_e32 v[48:49], 0
	v_mov_b64_e32 v[50:51], 0
	v_mov_b64_e32 v[52:53], 0
	v_mov_b64_e32 v[54:55], 0
	v_mov_b64_e32 v[56:57], 0
	v_mov_b64_e32 v[58:59], 0
	v_mov_b64_e32 v[60:61], 0
	v_mov_b64_e32 v[62:63], 0
	v_mov_b64_e32 v[64:65], 0
	v_mov_b64_e32 v[66:67], 0
	v_mov_b64_e32 v[68:69], 0
	v_mov_b64_e32 v[70:71], 0
	v_mov_b64_e32 v[72:73], 0
	v_mov_b64_e32 v[74:75], 0
	v_mov_b64_e32 v[76:77], 0
	v_mov_b64_e32 v[78:79], 0
	v_mov_b64_e32 v[80:81], 0
	v_mov_b64_e32 v[82:83], 0
	v_mov_b64_e32 v[88:89], 0
	v_mov_b64_e32 v[90:91], 0
	v_mov_b64_e32 v[98:99], 0
	v_mov_b64_e32 v[100:101], 0
	v_mov_b64_e32 v[106:107], 0
	v_mov_b64_e32 v[108:109], 0
	v_mov_b64_e32 v[84:85], 0
	v_mov_b64_e32 v[86:87], 0
	v_mov_b64_e32 v[92:93], 0
	v_mov_b64_e32 v[94:95], 0
	v_mov_b64_e32 v[102:103], 0
	v_mov_b64_e32 v[104:105], 0
	v_mov_b64_e32 v[110:111], 0
	v_mov_b64_e32 v[112:113], 0
	v_mov_b64_e32 v[114:115], 0
	v_mov_b64_e32 v[116:117], 0
	v_mov_b64_e32 v[118:119], 0
	v_mov_b64_e32 v[120:121], 0
	v_mov_b64_e32 v[122:123], 0
	v_mov_b64_e32 v[124:125], 0
	v_mov_b64_e32 v[126:127], 0
	v_mov_b64_e32 v[128:129], 0

.LBB0_697:
	s_or_b64 exec, exec, s[8:9]
	s_or_b32 s16, s30, s22
	s_lshl_b32 s2, s16, 19
	s_add_u32 s8, s23, s2
	v_mov_b32_e32 v0, 0
	s_addc_u32 s9, s24, 0
	s_mov_b32 s17, 0
	s_mov_b32 s18, 0
	v_mov_b32_e32 v1, v0
	v_mov_b64_e32 v[2:3], 0
	s_waitcnt lgkmcnt(0)
	s_barrier

.LBB0_1370:
	s_cmp_lg_u32 s56, 0
	s_cselect_b32 s11, s56, 16
	s_add_i32 s15, s11, -2
	s_add_u32 s24, s24, 0x40080
	s_addc_u32 s25, s25, 0
	s_add_u32 s17, s26, 0x100
	v_mov_b32_e32 v0, 0
	s_mov_b32 s44, 0
	s_addc_u32 s19, s27, 0
	v_mov_b32_e32 v1, v0
	v_mov_b64_e32 v[2:3], 0
	v_mov_b64_e32 v[4:5], 0
	v_mov_b64_e32 v[6:7], 0
	v_mov_b64_e32 v[8:9], 0
	v_mov_b64_e32 v[10:11], 0
	v_mov_b64_e32 v[16:17], 0
	v_mov_b64_e32 v[18:19], 0
	v_mov_b64_e32 v[24:25], 0
	v_mov_b64_e32 v[26:27], 0
	v_mov_b64_e32 v[32:33], 0
	v_mov_b64_e32 v[34:35], 0
	v_mov_b64_e32 v[40:41], 0
	v_mov_b64_e32 v[42:43], 0
	v_mov_b64_e32 v[48:49], 0
	v_mov_b64_e32 v[50:51], 0
	v_mov_b64_e32 v[12:13], 0
	v_mov_b64_e32 v[14:15], 0
	v_mov_b64_e32 v[20:21], 0
	v_mov_b64_e32 v[22:23], 0
	v_mov_b64_e32 v[28:29], 0
	v_mov_b64_e32 v[30:31], 0
	v_mov_b64_e32 v[36:37], 0
	v_mov_b64_e32 v[38:39], 0
	v_mov_b64_e32 v[44:45], 0
	v_mov_b64_e32 v[46:47], 0
	v_mov_b64_e32 v[52:53], 0
	v_mov_b64_e32 v[54:55], 0
	v_mov_b64_e32 v[56:57], 0
	v_mov_b64_e32 v[58:59], 0
	v_mov_b64_e32 v[60:61], 0
	v_mov_b64_e32 v[62:63], 0
	v_mov_b64_e32 v[64:65], 0
	v_mov_b64_e32 v[66:67], 0
	v_mov_b64_e32 v[68:69], 0
	v_mov_b64_e32 v[70:71], 0
	v_mov_b64_e32 v[72:73], 0
	v_mov_b64_e32 v[74:75], 0
	v_mov_b64_e32 v[80:81], 0
	v_mov_b64_e32 v[82:83], 0
	v_mov_b64_e32 v[88:89], 0
	v_mov_b64_e32 v[90:91], 0
	v_mov_b64_e32 v[98:99], 0
	v_mov_b64_e32 v[100:101], 0
	v_mov_b64_e32 v[106:107], 0
	v_mov_b64_e32 v[108:109], 0
	v_mov_b64_e32 v[114:115], 0
	v_mov_b64_e32 v[116:117], 0
	v_mov_b64_e32 v[76:77], 0
	v_mov_b64_e32 v[78:79], 0
	v_mov_b64_e32 v[84:85], 0
	v_mov_b64_e32 v[86:87], 0
	v_mov_b64_e32 v[92:93], 0
	v_mov_b64_e32 v[94:95], 0
	v_mov_b64_e32 v[102:103], 0
	v_mov_b64_e32 v[104:105], 0
	v_mov_b64_e32 v[110:111], 0
	v_mov_b64_e32 v[112:113], 0
	v_mov_b64_e32 v[118:119], 0
	v_mov_b64_e32 v[120:121], 0
	v_mov_b64_e32 v[122:123], 0
	v_mov_b64_e32 v[124:125], 0
	v_mov_b64_e32 v[126:127], 0
	v_mov_b64_e32 v[128:129], 0
	s_mov_b64 s[60:61], 0x80

.LBB0_1515:
	s_ashr_i32 s45, s44, 31
	s_lshl_b64 s[2:3], s[44:45], 19
	s_add_u32 s52, s28, s2
	s_addc_u32 s53, s64, s3
	s_and_b64 s[2:3], s[48:49], exec
	s_cselect_b32 s37, s53, s63
	s_cselect_b32 s45, s52, s62
	s_ashr_i32 s51, s50, 31
	s_lshl_b64 s[2:3], s[50:51], 19
	s_add_u32 s54, s65, s2
	s_addc_u32 s55, s66, s3
	s_and_b64 s[2:3], s[48:49], exec
	s_cselect_b32 s51, s55, s61
	s_cselect_b32 s57, s54, s60
	s_add_u32 s4, s62, 0x40080
	s_addc_u32 s5, s63, 0
	s_add_u32 s59, s60, 0x100
	v_mov_b32_e32 v0, 0
	s_addc_u32 s83, s61, 0
	s_mov_b32 s84, -2
	v_mov_b32_e32 v1, v0
	v_mov_b64_e32 v[2:3], 0
	v_mov_b64_e32 v[64:65], 0
	v_mov_b64_e32 v[66:67], 0
	v_mov_b64_e32 v[60:61], 0
	v_mov_b64_e32 v[62:63], 0
	v_mov_b64_e32 v[142:143], 0
	v_mov_b64_e32 v[144:145], 0
	v_mov_b64_e32 v[52:53], 0
	v_mov_b64_e32 v[54:55], 0
	v_mov_b64_e32 v[4:5], 0
	v_mov_b64_e32 v[6:7], 0
	v_mov_b64_e32 v[12:13], 0
	v_mov_b64_e32 v[14:15], 0
	v_mov_b64_e32 v[76:77], 0
	v_mov_b64_e32 v[78:79], 0
	v_mov_b64_e32 v[20:21], 0
	v_mov_b64_e32 v[22:23], 0
	v_mov_b64_e32 v[84:85], 0
	v_mov_b64_e32 v[86:87], 0
	v_mov_b64_e32 v[28:29], 0
	v_mov_b64_e32 v[30:31], 0
	v_mov_b64_e32 v[92:93], 0
	v_mov_b64_e32 v[94:95], 0
	v_mov_b64_e32 v[68:69], 0
	v_mov_b64_e32 v[70:71], 0
	v_mov_b64_e32 v[8:9], 0
	v_mov_b64_e32 v[10:11], 0
	v_mov_b64_e32 v[72:73], 0
	v_mov_b64_e32 v[74:75], 0
	v_mov_b64_e32 v[16:17], 0
	v_mov_b64_e32 v[18:19], 0
	v_mov_b64_e32 v[80:81], 0
	v_mov_b64_e32 v[82:83], 0
	v_mov_b64_e32 v[24:25], 0
	v_mov_b64_e32 v[26:27], 0
	v_mov_b64_e32 v[88:89], 0
	v_mov_b64_e32 v[90:91], 0
	v_mov_b64_e32 v[32:33], 0
	v_mov_b64_e32 v[34:35], 0
	v_mov_b64_e32 v[98:99], 0
	v_mov_b64_e32 v[100:101], 0
	v_mov_b64_e32 v[44:45], 0
	v_mov_b64_e32 v[46:47], 0
	v_mov_b64_e32 v[110:111], 0
	v_mov_b64_e32 v[112:113], 0
	v_mov_b64_e32 v[56:57], 0
	v_mov_b64_e32 v[58:59], 0
	v_mov_b64_e32 v[134:135], 0
	v_mov_b64_e32 v[136:137], 0
	v_mov_b64_e32 v[36:37], 0
	v_mov_b64_e32 v[38:39], 0
	v_mov_b64_e32 v[102:103], 0
	v_mov_b64_e32 v[104:105], 0
	v_mov_b64_e32 v[40:41], 0
	v_mov_b64_e32 v[42:43], 0
	v_mov_b64_e32 v[106:107], 0
	v_mov_b64_e32 v[108:109], 0
	v_mov_b64_e32 v[48:49], 0
	v_mov_b64_e32 v[50:51], 0
	v_mov_b64_e32 v[114:115], 0
	v_mov_b64_e32 v[116:117], 0
	v_mov_b64_e32 v[138:139], 0
	v_mov_b64_e32 v[140:141], 0
	v_readlane_b32 s39, v255, 15
	s_mov_b64 vcc, 0x80

.LBB0_1780:
	s_cmp_lg_u32 s60, 0
	s_cselect_b32 s11, s60, 64
	s_add_i32 s15, s11, -2
	s_add_u32 s24, s24, 0x100080
	s_addc_u32 s25, s25, 0
	s_add_u32 s17, s26, 0x100
	v_mov_b32_e32 v0, 0
	s_mov_b32 s50, 0
	s_addc_u32 s19, s27, 0
	v_mov_b32_e32 v1, v0
	v_mov_b64_e32 v[2:3], 0
	v_mov_b64_e32 v[4:5], 0
	v_mov_b64_e32 v[6:7], 0
	v_mov_b64_e32 v[8:9], 0
	v_mov_b64_e32 v[10:11], 0
	v_mov_b64_e32 v[16:17], 0
	v_mov_b64_e32 v[18:19], 0
	v_mov_b64_e32 v[24:25], 0
	v_mov_b64_e32 v[26:27], 0
	v_mov_b64_e32 v[32:33], 0
	v_mov_b64_e32 v[34:35], 0
	v_mov_b64_e32 v[40:41], 0
	v_mov_b64_e32 v[42:43], 0
	v_mov_b64_e32 v[48:49], 0
	v_mov_b64_e32 v[50:51], 0
	v_mov_b64_e32 v[12:13], 0
	v_mov_b64_e32 v[14:15], 0
	v_mov_b64_e32 v[20:21], 0
	v_mov_b64_e32 v[22:23], 0
	v_mov_b64_e32 v[28:29], 0
	v_mov_b64_e32 v[30:31], 0
	v_mov_b64_e32 v[36:37], 0
	v_mov_b64_e32 v[38:39], 0
	v_mov_b64_e32 v[44:45], 0
	v_mov_b64_e32 v[46:47], 0
	v_mov_b64_e32 v[52:53], 0
	v_mov_b64_e32 v[54:55], 0
	v_mov_b64_e32 v[56:57], 0
	v_mov_b64_e32 v[58:59], 0
	v_mov_b64_e32 v[60:61], 0
	v_mov_b64_e32 v[62:63], 0
	v_mov_b64_e32 v[64:65], 0
	v_mov_b64_e32 v[66:67], 0
	v_mov_b64_e32 v[68:69], 0
	v_mov_b64_e32 v[70:71], 0
	v_mov_b64_e32 v[72:73], 0
	v_mov_b64_e32 v[74:75], 0
	v_mov_b64_e32 v[80:81], 0
	v_mov_b64_e32 v[82:83], 0
	v_mov_b64_e32 v[88:89], 0
	v_mov_b64_e32 v[90:91], 0
	v_mov_b64_e32 v[98:99], 0
	v_mov_b64_e32 v[100:101], 0
	v_mov_b64_e32 v[106:107], 0
	v_mov_b64_e32 v[108:109], 0
	v_mov_b64_e32 v[114:115], 0
	v_mov_b64_e32 v[116:117], 0
	v_mov_b64_e32 v[76:77], 0
	v_mov_b64_e32 v[78:79], 0
	v_mov_b64_e32 v[84:85], 0
	v_mov_b64_e32 v[86:87], 0
	v_mov_b64_e32 v[92:93], 0
	v_mov_b64_e32 v[94:95], 0
	v_mov_b64_e32 v[102:103], 0
	v_mov_b64_e32 v[104:105], 0
	v_mov_b64_e32 v[110:111], 0
	v_mov_b64_e32 v[112:113], 0
	v_mov_b64_e32 v[118:119], 0
	v_mov_b64_e32 v[120:121], 0
	v_mov_b64_e32 v[122:123], 0
	v_mov_b64_e32 v[124:125], 0
	v_mov_b64_e32 v[126:127], 0
	v_mov_b64_e32 v[128:129], 0
	s_mov_b64 s[64:65], 0x80
